# diff exp block: add-zero packed add merged into the next packed add (one packed op fewer per tile), otherwise identical to v_m36
# baseline (speedup 1.0000x reference)
.LBB0_52:
	v_exp_f32_e32 v194, v167
	v_exp_f32_e32 v168, v168
	v_exp_f32_e32 v204, v163
	v_exp_f32_e32 v208, v159
	v_exp_f32_e32 v166, v166
	v_exp_f32_e32 v202, v169
	v_exp_f32_e32 v164, v164
	v_exp_f32_e32 v160, v160
	v_exp_f32_e32 v212, v155
	v_exp_f32_e32 v167, v150
	v_exp_f32_e32 v216, v157
	v_exp_f32_e32 v195, v151
	v_exp_f32_e32 v169, v152
	v_exp_f32_e32 v203, v153
	v_exp_f32_e32 v162, v162
	v_exp_f32_e32 v206, v165
	v_exp_f32_e32 v163, v146
	v_exp_f32_e32 v205, v147
	v_pk_add_f32 v[150:151], v[194:195], v[166:167]
	v_exp_f32_e32 v165, v148
	v_pk_add_f32 v[150:151], v[168:169], v[150:151]
	v_exp_f32_e32 v207, v149
	v_pk_add_f32 v[150:151], v[202:203], v[150:151]
	v_exp_f32_e32 v158, v158
	v_exp_f32_e32 v210, v161
	v_pk_add_f32 v[150:151], v[162:163], v[150:151]
	v_exp_f32_e32 v159, v142
	v_pk_add_f32 v[150:151], v[204:205], v[150:151]
	v_exp_f32_e32 v209, v143
	v_exp_f32_e32 v156, v156
	v_pk_add_f32 v[150:151], v[164:165], v[150:151]
	v_exp_f32_e32 v161, v144
	v_exp_f32_e32 v155, v138
	v_pk_add_f32 v[150:151], v[206:207], v[150:151]
	v_exp_f32_e32 v211, v145
	v_exp_f32_e32 v213, v139
	v_exp_f32_e32 v154, v154
	v_exp_f32_e32 v157, v140
	v_pk_add_f32 v[138:139], v[158:159], v[150:151]
	v_pk_add_f32 v[138:139], v[208:209], v[138:139]
	v_exp_f32_e32 v217, v141
	v_pk_add_f32 v[138:139], v[160:161], v[138:139]
	v_cvt_pk_bf16_f32 v146, v166, v194
	v_pk_add_f32 v[138:139], v[210:211], v[138:139]
	v_cvt_pk_bf16_f32 v147, v168, v202
	v_pk_add_f32 v[138:139], v[154:155], v[138:139]
	v_cvt_pk_bf16_f32 v148, v162, v204
	v_pk_add_f32 v[138:139], v[212:213], v[138:139]
	v_cvt_pk_bf16_f32 v149, v164, v206
	v_pk_add_f32 v[138:139], v[156:157], v[138:139]
	v_cvt_pk_bf16_f32 v140, v154, v212
	v_pk_add_f32 v[142:143], v[216:217], v[138:139]
	v_cvt_pk_bf16_f32 v138, v158, v208
	v_cvt_pk_bf16_f32 v139, v160, v210
	v_cvt_pk_bf16_f32 v141, v156, v216
	v_max_f32_e32 v196, v142, v143
	v_cmp_lt_f32_e32 vcc, 0x47800000, v196
	s_cbranch_vccnz .Lmy_redo
